# R0 ctx rows: the rows' modulation vectors fetched with all 12 loads in flight (was four dependent groups)
# speedup vs baseline: 1.0159x; 1.0027x over previous
; __device__ __forceinline__ void load_mod(const float* normw, const float* mods, int ms, int shidx, int lane, f32x4 (&wv)[4], f32x4 (&shv)[4]) {
; #pragma unroll
;     for (int j = 0; j < 4; ++j) { const int c = 4 * lane + 256 * j;
;         const f32x4 w = *(const f32x4*)(normw + c), sc = *(const f32x4*)(mods + ms * (NMOD * D) + (shidx + 1) * D + c);
;         shv[j] = *(const f32x4*)(mods + ms * (NMOD * D) + shidx * D + c); wv[j] = w * (sc + 1.0f); }
; }
.LBB0_489:
	s_add_u32 s22, s6, 0x3d16000
	s_addc_u32 s23, s7, 0
	s_add_u32 s16, s6, 0x3d15000
	s_addc_u32 s17, s7, 0
	v_lshlrev_b32_e32 v206, 2, v128
	global_load_dwordx4 v[96:99], v206, s[22:23]
	global_load_dwordx4 v[112:115], v206, s[26:27]
	global_load_dwordx4 v[0:3], v206, s[16:17]
	global_load_dwordx4 v[100:103], v206, s[22:23] offset:1024
	global_load_dwordx4 v[116:119], v206, s[26:27] offset:1024
	global_load_dwordx4 v[4:7], v206, s[16:17] offset:1024
	global_load_dwordx4 v[104:107], v206, s[22:23] offset:2048
	global_load_dwordx4 v[120:123], v206, s[26:27] offset:2048
	global_load_dwordx4 v[8:11], v206, s[16:17] offset:2048
	global_load_dwordx4 v[108:111], v206, s[22:23] offset:3072
	global_load_dwordx4 v[124:127], v206, s[26:27] offset:3072
	global_load_dwordx4 v[12:15], v206, s[16:17] offset:3072
	s_load_dwordx2 s[10:11], s[10:11], 0x10
	s_ashr_i32 s9, s8, 31
	s_lshl_b64 s[4:5], s[8:9], 11
	v_xor_b32_e32 v53, 4, v128
	v_xor_b32_e32 v54, 8, v128
	v_xor_b32_e32 v55, 16, v128
	v_xor_b32_e32 v56, 32, v128
	v_xor_b32_e32 v57, 64, v128
	v_xor_b32_e32 v58, 0x80, v128
	v_mov_b32_e32 v33, s5
	v_or_b32_e32 v32, s4, v68
	s_lshl_b64 s[4:5], s[8:9], 12
	v_lshl_or_b32 v34, v67, 4, s4
	v_mov_b32_e32 v35, s5
	v_readlane_b32 s4, v254, 55
	s_mov_b32 s12, s4
	v_readlane_b32 s5, v254, 56
	s_waitcnt vmcnt(0)
	v_pk_add_f32 v[96:97], v[96:97], 1.0 op_sel_hi:[1,0]
	v_pk_add_f32 v[98:99], v[98:99], 1.0 op_sel_hi:[1,0]
	v_pk_mul_f32 v[18:19], v[112:113], v[96:97]
	v_pk_mul_f32 v[16:17], v[114:115], v[98:99]
	v_pk_add_f32 v[100:101], v[100:101], 1.0 op_sel_hi:[1,0]
	v_pk_add_f32 v[102:103], v[102:103], 1.0 op_sel_hi:[1,0]
	v_pk_mul_f32 v[22:23], v[116:117], v[100:101]
	v_pk_mul_f32 v[20:21], v[118:119], v[102:103]
	v_pk_add_f32 v[104:105], v[104:105], 1.0 op_sel_hi:[1,0]
	v_pk_add_f32 v[106:107], v[106:107], 1.0 op_sel_hi:[1,0]
	v_pk_mul_f32 v[26:27], v[120:121], v[104:105]
	v_pk_mul_f32 v[24:25], v[122:123], v[106:107]
	v_pk_add_f32 v[108:109], v[108:109], 1.0 op_sel_hi:[1,0]
	v_pk_add_f32 v[110:111], v[110:111], 1.0 op_sel_hi:[1,0]
	v_pk_mul_f32 v[30:31], v[124:125], v[108:109]
	v_pk_mul_f32 v[28:29], v[126:127], v[110:111]
